# v30 + attention tile loops: relative-position bias + causal mask for near tiles via a NEG-padded per-map LDS table read with immediate offsets from one per-lane base (32 ds_read_b32 + 32 adds instead
# speedup vs baseline: 1.0164x; 1.0095x over previous
; __device__ __forceinline__ void diff_unit(int b, int hd, int qb, const bf16_t* Q, const bf16_t* K, const bf16_t* VT, bf16_t* O, const float* biasd, float lam, const float* subg, ALAS unsigned char* lds) {
;     ...
;     const int tid = tid_, lane = tid & 63, wid = __builtin_amdgcn_readfirstlane(tid >> 6), r32 = lane & 31, hi = lane >> 5;
;     const int map = wid >> 2, w4 = wid & 3, q0 = qb * 128 + w4 * 32, qpos = q0 + r32;
;     if (wid >= 4) __builtin_amdgcn_s_setprio(1);
;     const size_t tok0 = (size_t)b * SEQ;
;     ALAS float* btab = (ALAS float*)(lds + 73728);
;     btab[tid] = biasd[(2 * hd) * 256 + tid];
;     const ALAS float* bt = btab + map * 256;
;     const float cb = biasd[(2 * hd + map) * 256 + 255];
;     bf16x8 qf[4];
;     { const bf16_t* qp = Q + (tok0 + qpos) * 1024 + (2 * hd + map) * 64 + hi * 8;
; #pragma unroll
;       for (int d0 = 0; d0 < 4; ++d0) qf[d0] = *(const bf16x8*)(qp + d0 * 16); }
;     const int NT = 2 * (qb + 1);
;     const bf16_t* kg[2]; const bf16_t* vg[2]; int kl[2], vl[2];
; #pragma unroll
;     for (int i = 0; i < 2; ++i) { const int c = tid + 512 * i; const int key = c >> 4, part = c & 15;
;         kg[i] = K + (tok0 + key) * 1024 + hd * 128 + part * 8; kl[i] = ((part >> 3) * 64 + key) * ROWB + (part & 7) * 16;
;         const int d = c >> 3, pv = c & 7; vg[i] = VT + (size_t)(hd * 128 + d) * MTOK + tok0 + pv * 8; vl[i] = 18432 + d * ROWB + pv * 16; }
;     u32x4 kr[2], vr[2];
; #pragma unroll
;     for (int i = 0; i < 2; ++i) { kr[i] = *(const u32x4*)(kg[i]); vr[i] = *(const u32x4*)(vg[i]); }
;     f32x16 o[4]; float mref = 0.f, lsum = 0.f;
; #pragma unroll
;     for (int d = 0; d < 4; ++d)
; #pragma unroll
;         for (int r = 0; r < 16; ++r) o[d][r] = 0.f;
;     for (int t = 0; t < NT; ++t) {
;         ALAS unsigned char* buf = lds + (t & 1) * 36864;
; #pragma unroll
;         for (int i = 0; i < 2; ++i) { *(ALAS u32x4*)(buf + kl[i]) = kr[i]; *(ALAS u32x4*)(buf + vl[i]) = vr[i]; }
;         __syncthreads();
;         if (t + 1 < NT) {
; #pragma unroll
;             for (int i = 0; i < 2; ++i) { kr[i] = *(const u32x4*)(kg[i] + (size_t)(t + 1) * 64 * 1024); vr[i] = *(const u32x4*)(vg[i] + (t + 1) * 64); }
;         }
;         const int kbase = 64 * t;
;         if (kbase <= q0 + 31) {
;             const bool far = (q0 - (kbase + 63)) >= 128;
;             f32x16 s0, s1; const float ci = (far ? cb : 0.f) - mref;
.LBB0_497:
	s_ashr_i32 s9, s1, 6
	s_and_b32 s6, s1, 3
	s_and_b32 s9, s9, -8
	s_or_b32 s6, s9, s6
	s_and_b32 s8, s1, 0x100
	s_xor_b32 s9, s6, 7
	s_cmp_eq_u32 s8, 0
	s_cselect_b32 s14, s6, s9
	s_bfe_u32 s10, s1, 0x30002
	v_lshl_add_u32 v0, s10, 9, v135
	v_ashrrev_i32_e32 v1, 31, v0
	v_lshl_add_u64 v[0:1], v[0:1], 2, s[96:97]
	global_load_dword v0, v[0:1], off
	s_and_b32 s8, s4, 3
	s_lshl_b32 s12, s14, 7
	s_lshl_b32 s13, s8, 5
	v_and_b32_e32 v70, 31, v135
	s_or_b32 s15, s13, s12
	v_or_b32_e32 v136, s15, v70
	s_lshl_b32 s4, s1, 7
	v_lshl_add_u32 v1, v135, 2, 0
	s_and_b32 s4, s4, 0x7000
	v_add_u32_e32 v1, 0x12000, v1
	v_ashrrev_i32_e32 v137, 31, v136
	v_bfe_u32 v2, v135, 5, 1
	s_ashr_i32 s9, s7, 8
	s_lshl_b32 s6, s10, 7
	s_cmp_lt_i32 s14, 0
	v_lshlrev_b32_e32 v134, 3, v2
	v_lshlrev_b32_e32 v130, 4, v2
	v_lshrrev_b32_e32 v3, 8, v135
	v_lshl_add_u32 v3, v3, 10, v1
	s_waitcnt vmcnt(0)
	ds_write_b32 v1, v0
	ds_write_b32 v3, v0 offset:3072
	ds_write_b32 v3, v205 offset:2048
	v_lshl_add_u64 v[0:1], v[136:137], 0, s[4:5]
	v_lshlrev_b64 v[132:133], 10, v[0:1]
	s_cbranch_scc1 .LBB0_511
	s_lshl_b32 s10, s10, 1
	s_add_i32 s17, s9, s10
	s_lshl_b32 s10, s17, 8
	s_ashr_i32 s11, s10, 31
	s_and_b32 s16, s7, 0x3fffff00
	s_lshl_b64 s[10:11], s[10:11], 2
	s_add_u32 s10, s96, s10
	s_addc_u32 s11, s97, s11
	global_load_dword v137, v145, s[10:11] offset:1020
	s_lshl_b32 s10, s6, 1
	s_add_u32 s10, s82, s10
	v_lshlrev_b32_e32 v1, 4, v135
	s_addc_u32 s11, s83, 0
	v_and_b32_e32 v144, 0xf0, v1
	v_lshlrev_b32_e32 v0, 3, v135
	v_lshl_add_u64 v[2:3], s[10:11], 0, v[144:145]
	s_lshl_b32 s10, s4, 1
	v_and_b32_e32 v8, 64, v0
	s_add_u32 s10, s20, s10
	v_ashrrev_i32_e32 v64, 4, v135
	v_and_b32_e32 v20, 0x70, v1
	s_addc_u32 s11, s21, 0
	v_mov_b32_e32 v21, v145
	v_add_u32_e32 v6, v8, v64
	s_movk_i32 s18, 0x90
	v_lshl_add_u64 v[4:5], s[10:11], 0, v[20:21]
	v_mad_u64_u32 v[138:139], s[10:11], v6, s18, v[20:21]
	v_ashrrev_i32_e32 v21, 3, v135
	v_add_u32_e32 v6, s6, v21
	v_add_u32_e32 v9, 0x200, v135
	v_ashrrev_i32_e32 v7, 31, v6
	v_ashrrev_i32_e32 v66, 4, v9
	v_ashrrev_i32_e32 v65, 31, v64
	v_lshlrev_b64 v[6:7], 16, v[6:7]
	v_ashrrev_i32_e32 v67, 31, v66
	v_lshl_add_u64 v[0:1], v[64:65], 0, s[4:5]
	v_lshl_add_u64 v[140:141], v[4:5], 0, v[6:7]
	v_lshl_add_u64 v[6:7], v[66:67], 0, s[4:5]
	v_lshlrev_b64 v[0:1], 11, v[0:1]
	v_lshlrev_b64 v[6:7], 11, v[6:7]
	v_lshl_add_u64 v[0:1], v[2:3], 0, v[0:1]
	v_lshl_add_u64 v[2:3], v[2:3], 0, v[6:7]
	v_add_u32_e32 v6, v66, v8
	v_ashrrev_i32_e32 v22, 3, v9
	v_mad_u64_u32 v[142:143], s[10:11], v6, s18, v[20:21]
	v_add_u32_e32 v6, s6, v22
	v_ashrrev_i32_e32 v7, 31, v6
	v_lshlrev_b64 v[6:7], 16, v[6:7]
	s_lshl_b32 s4, s16, 2
	s_lshl_b32 s16, s17, 6
	v_lshl_add_u64 v[156:157], v[4:5], 0, v[6:7]
	v_lshl_add_u64 v[4:5], v[132:133], 1, s[80:81]
	s_ashr_i32 s17, s16, 31
	v_lshl_add_u64 v[4:5], s[16:17], 1, v[4:5]
	v_mov_b32_e32 v131, v145
	v_lshl_add_u64 v[4:5], v[4:5], 0, v[130:131]
	global_load_dwordx4 v[96:99], v[4:5], off offset:96
	global_load_dwordx4 v[100:103], v[4:5], off offset:64
	global_load_dwordx4 v[104:107], v[4:5], off offset:32
	global_load_dwordx4 v[108:111], v[4:5], off
	s_nop 0
	global_load_dwordx4 v[4:7], v[156:157], off
	global_load_dwordx4 v[8:11], v[2:3], off
	global_load_dwordx4 v[12:15], v[140:141], off
	global_load_dwordx4 v[16:19], v[0:1], off
	v_lshlrev_b32_e32 v24, 1, v70
	v_lshrrev_b32_e32 v25, 1, v135
	v_and_b32_e32 v23, 19, v135
	v_and_b32_e32 v24, 8, v24
	v_and_b32_e32 v25, 4, v25
	v_or3_b32 v23, v25, v23, v24
	v_mul_u32_u24_e32 v139, 0x90, v23
	v_add_u32_e32 v23, 0, v138
	v_mad_u64_u32 v[158:159], s[16:17], v21, s18, v[20:21]
	s_add_i32 s10, s4, 0
	s_mov_b32 s4, 0x20000
	v_mad_u64_u32 v[160:161], s[16:17], v22, s18, v[20:21]
	v_add_co_u32_e32 v0, vcc, s4, v0
	s_add_i32 s10, s10, 0x12000
	s_nop 0
	v_addc_co_u32_e32 v1, vcc, 0, v1, vcc
	s_mul_i32 s11, s9, 0x2400
	s_cmpk_gt_i32 s15, 0xbe
	s_waitcnt vmcnt(0)
	ds_write_b128 v23, v[16:19]
	v_add_u32_e32 v16, 0, v158
	ds_write_b128 v16, v[12:15] offset:18432
	v_add_u32_e32 v12, 0, v142
	ds_write_b128 v12, v[8:11]
	v_add_u32_e32 v8, 0, v160
	ds_write_b128 v8, v[4:7] offset:18432
	s_waitcnt lgkmcnt(0)
	s_barrier
	global_load_dwordx4 v[112:115], v[0:1], off
	global_load_dwordx4 v[116:119], v[140:141], off offset:128
	v_add_co_u32_e32 v0, vcc, s4, v2
	s_nop 1
	v_addc_co_u32_e32 v1, vcc, 0, v3, vcc
	global_load_dwordx4 v[120:123], v[0:1], off
	global_load_dwordx4 v[124:127], v[156:157], off offset:128
	s_cselect_b64 vcc, -1, 0
	s_add_i32 s4, s11, 0
	v_add3_u32 v1, s4, v139, v130
	ds_read_b128 v[32:35], v1 offset:0
	ds_read_b128 v[36:39], v1 offset:4608
	ds_read_b128 v[40:43], v1 offset:32
	ds_read_b128 v[44:47], v1 offset:4640
	ds_read_b128 v[48:51], v1 offset:64
	ds_read_b128 v[52:55], v1 offset:4672
	ds_read_b128 v[56:59], v1 offset:96
	ds_read_b128 v[60:63], v1 offset:4704
	v_cndmask_b32_e32 v0, 0, v137, vcc
	v_mov_b32_e32 v1, v0
	v_mov_b32_e32 v2, v0
	v_mov_b32_e32 v3, v0
	v_mov_b32_e32 v4, v0
	v_mov_b32_e32 v5, v0
	v_mov_b32_e32 v6, v0
	v_mov_b32_e32 v7, v0
	v_mov_b32_e32 v8, v0
	v_mov_b32_e32 v9, v0
	v_mov_b32_e32 v10, v0
	v_mov_b32_e32 v11, v0
	v_mov_b32_e32 v12, v0
	v_mov_b32_e32 v13, v0
	v_mov_b32_e32 v14, v0
	v_mov_b32_e32 v15, v0
	s_waitcnt lgkmcnt(6)
	s_nop 1
	v_mfma_f32_32x32x16_bf16 v[16:31], v[32:35], v[108:111], v[0:15]
	s_and_b64 vcc, exec, vcc
	v_mfma_f32_32x32x16_bf16 v[0:15], v[36:39], v[108:111], v[0:15]
	s_waitcnt lgkmcnt(4)
	v_mfma_f32_32x32x16_bf16 v[16:31], v[40:43], v[104:107], v[16:31]
	v_mfma_f32_32x32x16_bf16 v[0:15], v[44:47], v[104:107], v[0:15]
	s_waitcnt lgkmcnt(2)
	v_mfma_f32_32x32x16_bf16 v[16:31], v[48:51], v[100:103], v[16:31]
	v_mfma_f32_32x32x16_bf16 v[0:15], v[52:55], v[100:103], v[0:15]
	s_waitcnt lgkmcnt(0)
	v_mfma_f32_32x32x16_bf16 v[16:31], v[56:59], v[96:99], v[16:31]
	v_mfma_f32_32x32x16_bf16 v[0:15], v[60:63], v[96:99], v[0:15]
	s_cbranch_vccnz .LBB0_500
; #define ALAS __attribute__((address_space(3)))
; __device__ __forceinline__ void near_bias(f32x16& s0, f32x16& s1, const ALAS float* bt, int qpos, int kbase, int hi) {
; #pragma unroll
;     for (int r = 0; r < 16; ++r) {
;         const int d0 = qpos - (kbase + (r & 7) + 8 * hi + 16 * (r >> 3)), d1 = d0 - 32;
;         const float b0 = bt[min(max(d0, 0), 255)], b1 = bt[min(max(d1, 0), 255)];
;         s0[r] = d0 < 0 ? NEG : s0[r] + b0; s1[r] = d1 < 0 ? NEG : s1[r] + b1;
;     }
; }
	v_xad_u32 v69, v134, -1, v136
	v_med3_i32 v34, v69, 0, v204
	v_lshl_add_u32 v35, v34, 2, s10
	v_max_i32_e32 v34, 32, v69
	v_subrev_u32_e32 v34, 32, v34
	v_min_u32_e32 v34, 0xff, v34
	v_or_b32_e32 v37, 2, v134
	v_lshl_add_u32 v36, v34, 2, s10
	v_or_b32_e32 v34, 3, v134
	v_sub_u32_e32 v72, v136, v37
	v_sub_u32_e32 v71, v136, v34
	v_med3_i32 v34, v72, 0, v204
	v_lshl_add_u32 v37, v34, 2, s10
	v_max_i32_e32 v34, 32, v72
	v_subrev_u32_e32 v34, 32, v34
	v_min_u32_e32 v34, 0xff, v34
	v_sub_u32_e32 v68, v136, v134
	v_lshl_add_u32 v38, v34, 2, s10
	v_max_i32_e32 v34, 32, v71
	v_max_i32_e32 v33, 32, v68
	v_subrev_u32_e32 v34, 32, v34
	v_subrev_u32_e32 v33, 32, v33
	v_min_u32_e32 v34, 0xff, v34
	v_med3_i32 v32, v68, 0, v204
	v_min_u32_e32 v33, 0xff, v33
	v_lshl_add_u32 v39, v34, 2, s10
	v_med3_i32 v34, v71, 0, v204
	v_lshl_add_u32 v32, v32, 2, s10
	v_lshl_add_u32 v33, v33, 2, s10
	v_lshl_add_u32 v40, v34, 2, s10
	ds_read_b32 v34, v32
	ds_read_b32 v32, v33
	ds_read_b32 v35, v35
	ds_read_b32 v33, v36
	ds_read_b32 v36, v37
	ds_read_b32 v38, v38
	ds_read_b32 v39, v39
	ds_read_b32 v37, v40
	v_or_b32_e32 v40, 5, v134
	v_sub_u32_e32 v73, v136, v40
	v_max_i32_e32 v42, 32, v73
	v_subrev_u32_e32 v42, 32, v42
	v_min_u32_e32 v42, 0xff, v42
	v_lshl_add_u32 v43, v42, 2, s10
	v_med3_i32 v42, v73, 0, v204
	v_or_b32_e32 v45, 6, v134
	v_lshl_add_u32 v44, v42, 2, s10
	v_or_b32_e32 v42, 7, v134
	v_sub_u32_e32 v76, v136, v45
	v_sub_u32_e32 v75, v136, v42
	v_med3_i32 v42, v76, 0, v204
	v_lshl_add_u32 v45, v42, 2, s10
	v_max_i32_e32 v42, 32, v76
	v_subrev_u32_e32 v42, 32, v42
	v_or_b32_e32 v41, 4, v134
	v_min_u32_e32 v42, 0xff, v42
	v_sub_u32_e32 v74, v136, v41
	v_lshl_add_u32 v46, v42, 2, s10
	v_max_i32_e32 v42, 32, v75
	v_max_i32_e32 v41, 32, v74
	v_subrev_u32_e32 v42, 32, v42
	v_subrev_u32_e32 v41, 32, v41
	v_min_u32_e32 v42, 0xff, v42
	v_med3_i32 v40, v74, 0, v204
	v_min_u32_e32 v41, 0xff, v41
	v_lshl_add_u32 v47, v42, 2, s10
	v_med3_i32 v42, v75, 0, v204
	v_lshl_add_u32 v40, v40, 2, s10
	v_lshl_add_u32 v41, v41, 2, s10
	v_lshl_add_u32 v48, v42, 2, s10
	ds_read_b32 v40, v40
	ds_read_b32 v42, v41
	ds_read_b32 v43, v43
	ds_read_b32 v41, v44
	ds_read_b32 v44, v45
	ds_read_b32 v46, v46
	ds_read_b32 v47, v47
	ds_read_b32 v45, v48
	v_or_b32_e32 v48, 17, v134
	v_sub_u32_e32 v77, v136, v48
	v_max_i32_e32 v50, 32, v77
	v_subrev_u32_e32 v50, 32, v50
	v_min_u32_e32 v50, 0xff, v50
	v_lshl_add_u32 v51, v50, 2, s10
	v_med3_i32 v50, v77, 0, v204
	v_or_b32_e32 v53, 18, v134
	v_lshl_add_u32 v52, v50, 2, s10
	v_or_b32_e32 v50, 19, v134
	v_sub_u32_e32 v80, v136, v53
	v_sub_u32_e32 v79, v136, v50
	v_med3_i32 v50, v80, 0, v204
	v_lshl_add_u32 v53, v50, 2, s10
	v_max_i32_e32 v50, 32, v80
	v_subrev_u32_e32 v50, 32, v50
	v_or_b32_e32 v49, 16, v134
	v_min_u32_e32 v50, 0xff, v50
	v_sub_u32_e32 v78, v136, v49
	v_lshl_add_u32 v54, v50, 2, s10
	v_max_i32_e32 v50, 32, v79
	v_max_i32_e32 v49, 32, v78
	v_subrev_u32_e32 v50, 32, v50
	v_subrev_u32_e32 v49, 32, v49
	v_min_u32_e32 v50, 0xff, v50
	v_med3_i32 v48, v78, 0, v204
	v_min_u32_e32 v49, 0xff, v49
	v_lshl_add_u32 v55, v50, 2, s10
	v_med3_i32 v50, v79, 0, v204
	v_lshl_add_u32 v48, v48, 2, s10
	v_lshl_add_u32 v49, v49, 2, s10
	v_lshl_add_u32 v56, v50, 2, s10
	ds_read_b32 v48, v48
	ds_read_b32 v50, v49
	ds_read_b32 v51, v51
	ds_read_b32 v49, v52
	ds_read_b32 v52, v53
	ds_read_b32 v54, v54
	ds_read_b32 v55, v55
	ds_read_b32 v53, v56
	v_or_b32_e32 v56, 21, v134
	v_sub_u32_e32 v81, v136, v56
	v_max_i32_e32 v58, 32, v81
	v_subrev_u32_e32 v58, 32, v58
	v_min_u32_e32 v58, 0xff, v58
	v_lshl_add_u32 v59, v58, 2, s10
	v_med3_i32 v58, v81, 0, v204
	v_or_b32_e32 v61, 22, v134
	v_lshl_add_u32 v60, v58, 2, s10
	v_or_b32_e32 v58, 23, v134
	v_sub_u32_e32 v84, v136, v61
	v_sub_u32_e32 v83, v136, v58
	v_med3_i32 v58, v84, 0, v204
	v_lshl_add_u32 v61, v58, 2, s10
	v_max_i32_e32 v58, 32, v84
	v_or_b32_e32 v57, 20, v134
	v_subrev_u32_e32 v58, 32, v58
	v_sub_u32_e32 v82, v136, v57
	v_min_u32_e32 v58, 0xff, v58
	v_max_i32_e32 v57, 32, v82
	v_lshl_add_u32 v62, v58, 2, s10
	v_max_i32_e32 v58, 32, v83
	v_subrev_u32_e32 v57, 32, v57
	v_subrev_u32_e32 v58, 32, v58
	v_med3_i32 v56, v82, 0, v204
	v_min_u32_e32 v57, 0xff, v57
	v_min_u32_e32 v58, 0xff, v58
	v_lshl_add_u32 v56, v56, 2, s10
	v_lshl_add_u32 v57, v57, 2, s10
	v_lshl_add_u32 v63, v58, 2, s10
	v_med3_i32 v58, v83, 0, v204
	v_lshl_add_u32 v85, v58, 2, s10
	ds_read_b32 v56, v56
	ds_read_b32 v58, v57
	ds_read_b32 v59, v59
	ds_read_b32 v57, v60
	ds_read_b32 v60, v61
	ds_read_b32 v62, v62
	ds_read_b32 v63, v63
	ds_read_b32 v61, v85
	s_waitcnt lgkmcnt(14)
; __device__ __forceinline__ void near_bias(f32x16& s0, f32x16& s1, const ALAS float* bt, int qpos, int kbase, int hi) {
;     ...
;     for (int r = 0; r < 16; ++r) {
;         const int d0 = qpos - (kbase + (r & 7) + 8 * hi + 16 * (r >> 3)), d1 = d0 - 32;
;         const float b0 = bt[min(max(d0, 0), 255)], b1 = bt[min(max(d1, 0), 255)];
;         s0[r] = d0 < 0 ? NEG : s0[r] + b0; s1[r] = d1 < 0 ? NEG : s1[r] + b1;
;     }
	v_pk_add_f32 v[16:17], v[16:17], v[34:35]
	v_cmp_lt_i32_e32 vcc, -1, v69
	s_waitcnt lgkmcnt(4)
	v_pk_add_f32 v[28:29], v[28:29], v[56:57]
	v_pk_add_f32 v[26:27], v[26:27], v[52:53]
	s_waitcnt lgkmcnt(0)
	v_pk_add_f32 v[30:31], v[30:31], v[60:61]
	v_cndmask_b32_e32 v17, v205, v17, vcc
	v_cmp_lt_i32_e32 vcc, -1, v83
	v_pk_add_f32 v[24:25], v[24:25], v[48:49]
	v_pk_add_f32 v[22:23], v[22:23], v[44:45]
	v_cndmask_b32_e32 v31, v205, v31, vcc
	v_cmp_lt_i32_e32 vcc, -1, v84
	v_pk_add_f32 v[20:21], v[20:21], v[40:41]
	v_pk_add_f32 v[18:19], v[18:19], v[36:37]
	v_cndmask_b32_e32 v30, v205, v30, vcc
	v_cmp_lt_i32_e32 vcc, -1, v81
	v_pk_add_f32 v[0:1], v[0:1], v[32:33]
	v_pk_add_f32 v[14:15], v[14:15], v[62:63]
	v_cndmask_b32_e32 v29, v205, v29, vcc
	v_cmp_lt_i32_e32 vcc, -1, v82
	v_pk_add_f32 v[12:13], v[12:13], v[58:59]
	v_pk_add_f32 v[10:11], v[10:11], v[54:55]
	v_cndmask_b32_e32 v28, v205, v28, vcc
	v_cmp_lt_i32_e32 vcc, -1, v79
	v_pk_add_f32 v[8:9], v[8:9], v[50:51]
	v_pk_add_f32 v[6:7], v[6:7], v[46:47]
	v_cndmask_b32_e32 v27, v205, v27, vcc
	v_cmp_lt_i32_e32 vcc, -1, v80
	v_pk_add_f32 v[4:5], v[4:5], v[42:43]
	v_pk_add_f32 v[2:3], v[2:3], v[38:39]
	v_cndmask_b32_e32 v26, v205, v26, vcc
	v_cmp_lt_i32_e32 vcc, -1, v77
	s_nop 1
	v_cndmask_b32_e32 v25, v205, v25, vcc
	v_cmp_lt_i32_e32 vcc, -1, v78
	s_nop 1
	v_cndmask_b32_e32 v24, v205, v24, vcc
	v_cmp_lt_i32_e32 vcc, -1, v75
	s_nop 1
	v_cndmask_b32_e32 v23, v205, v23, vcc
	v_cmp_lt_i32_e32 vcc, -1, v76
	s_nop 1
	v_cndmask_b32_e32 v22, v205, v22, vcc
	v_cmp_lt_i32_e32 vcc, -1, v73
	s_nop 1
	v_cndmask_b32_e32 v21, v205, v21, vcc
	v_cmp_lt_i32_e32 vcc, -1, v74
	s_nop 1
	v_cndmask_b32_e32 v20, v205, v20, vcc
	v_cmp_lt_i32_e32 vcc, -1, v71
	s_nop 1
	v_cndmask_b32_e32 v19, v205, v19, vcc
	v_cmp_lt_i32_e32 vcc, -1, v72
	s_nop 1
	v_cndmask_b32_e32 v18, v205, v18, vcc
	v_cmp_lt_i32_e32 vcc, -1, v68
	s_nop 1
	v_cndmask_b32_e32 v16, v205, v16, vcc
	v_cmp_lt_i32_e32 vcc, 31, v69
	s_nop 1
	v_cndmask_b32_e32 v1, v205, v1, vcc
	v_cmp_lt_i32_e32 vcc, 31, v83
	s_nop 1
	v_cndmask_b32_e32 v15, v205, v15, vcc
	v_cmp_lt_i32_e32 vcc, 31, v84
	s_nop 1
	v_cndmask_b32_e32 v14, v205, v14, vcc
	v_cmp_lt_i32_e32 vcc, 31, v81
	s_nop 1
	v_cndmask_b32_e32 v13, v205, v13, vcc
	v_cmp_lt_i32_e32 vcc, 31, v82
	s_nop 1
	v_cndmask_b32_e32 v12, v205, v12, vcc
	v_cmp_lt_i32_e32 vcc, 31, v79
	s_nop 1
	v_cndmask_b32_e32 v11, v205, v11, vcc
	v_cmp_lt_i32_e32 vcc, 31, v80
	s_nop 1
	v_cndmask_b32_e32 v10, v205, v10, vcc
	v_cmp_lt_i32_e32 vcc, 31, v77
	s_nop 1
	v_cndmask_b32_e32 v9, v205, v9, vcc
	v_cmp_lt_i32_e32 vcc, 31, v78
	s_nop 1
	v_cndmask_b32_e32 v8, v205, v8, vcc
	v_cmp_lt_i32_e32 vcc, 31, v75
	s_nop 1
	v_cndmask_b32_e32 v7, v205, v7, vcc
	v_cmp_lt_i32_e32 vcc, 31, v76
	s_nop 1
	v_cndmask_b32_e32 v6, v205, v6, vcc
	v_cmp_lt_i32_e32 vcc, 31, v73
	s_nop 1
	v_cndmask_b32_e32 v5, v205, v5, vcc
	v_cmp_lt_i32_e32 vcc, 31, v74
	s_nop 1
	v_cndmask_b32_e32 v4, v205, v4, vcc
	v_cmp_lt_i32_e32 vcc, 31, v71
	s_nop 1
	v_cndmask_b32_e32 v3, v205, v3, vcc
	v_cmp_lt_i32_e32 vcc, 31, v72
	s_nop 1
	v_cndmask_b32_e32 v2, v205, v2, vcc
	v_cmp_lt_i32_e32 vcc, 31, v68
	s_nop 1
	v_cndmask_b32_e32 v0, v205, v0, vcc

; #define ALAS __attribute__((address_space(3)))
; __device__ __forceinline__ void near_bias(f32x16& s0, f32x16& s1, const ALAS float* bt, int qpos, int kbase, int hi) {
; #pragma unroll
;     for (int r = 0; r < 16; ++r) {
;         const int d0 = qpos - (kbase + (r & 7) + 8 * hi + 16 * (r >> 3)), d1 = d0 - 32;
;         const float b0 = bt[min(max(d0, 0), 255)], b1 = bt[min(max(d1, 0), 255)];
;         s0[r] = d0 < 0 ? NEG : s0[r] + b0; s1[r] = d1 < 0 ? NEG : s1[r] + b1;
;     }
; }
; __device__ __forceinline__ void diff_unit(int b, int hd, int qb, const bf16_t* Q, const bf16_t* K, const bf16_t* VT, bf16_t* O, const float* biasd, float lam, const float* subg, ALAS unsigned char* lds) {
;     ...
;         const int kbase = 64 * t;
;         if (kbase <= q0 + 31) {
;             const bool far = (q0 - (kbase + 63)) >= 128;
;             f32x16 s0, s1; const float ci = (far ? cb : 0.f) - mref;
;             qk_tile(s0, s1, ci, buf + map * 9216, qf, r32, hi);
;             if (!far) near_bias(s0, s1, bt, qpos, kbase, hi);
.LBB0_506:
	s_cmp_gt_i32 s17, s15
	s_cbranch_scc1 .LBB0_503
	s_cmpk_gt_i32 s12, 0x7f
	s_cselect_b64 vcc, -1, 0
	s_nop 1
	v_cndmask_b32_e32 v64, 0, v137, vcc
	v_sub_f32_e32 v64, v64, v163
	v_mov_b32_e32 v65, v64
	v_mov_b32_e32 v66, v64
	v_mov_b32_e32 v67, v64
	v_mov_b32_e32 v68, v64
	v_mov_b32_e32 v69, v64
	v_mov_b32_e32 v70, v64
	v_mov_b32_e32 v71, v64
	v_mov_b32_e32 v72, v64
	v_mov_b32_e32 v73, v64
	v_mov_b32_e32 v74, v64
	v_mov_b32_e32 v75, v64
	v_mov_b32_e32 v76, v64
	v_mov_b32_e32 v77, v64
	v_mov_b32_e32 v78, v64
	v_mov_b32_e32 v79, v64
	s_waitcnt lgkmcnt(6)
	s_nop 1
	v_mfma_f32_32x32x16_bf16 v[80:95], v[172:175], v[108:111], v[64:79]
	s_and_b64 vcc, exec, vcc
	v_mfma_f32_32x32x16_bf16 v[64:79], v[176:179], v[108:111], v[64:79]
	s_waitcnt lgkmcnt(4)
	v_mfma_f32_32x32x16_bf16 v[80:95], v[180:183], v[104:107], v[80:95]
	v_mfma_f32_32x32x16_bf16 v[64:79], v[184:187], v[104:107], v[64:79]
	s_waitcnt lgkmcnt(2)
	v_mfma_f32_32x32x16_bf16 v[80:95], v[188:191], v[100:103], v[80:95]
	v_mfma_f32_32x32x16_bf16 v[64:79], v[192:195], v[100:103], v[64:79]
	s_waitcnt lgkmcnt(0)
	v_mfma_f32_32x32x16_bf16 v[80:95], v[196:199], v[96:99], v[80:95]
	v_mfma_f32_32x32x16_bf16 v[64:79], v[216:219], v[96:99], v[64:79]
	s_cbranch_vccnz .LBB0_509
	v_add_u32_e32 v161, s12, v159
	v_lshlrev_b32_e32 v161, 2, v161
	s_lshl_b32 s4, s9, 11
	s_add_i32 s4, s4, 0x12c20
	v_add_u32_e32 v161, s4, v161
	ds_read_b32 v172, v161 offset:92
	ds_read_b32 v173, v161 offset:88
	ds_read_b32 v174, v161 offset:84
	ds_read_b32 v175, v161 offset:80
	ds_read_b32 v176, v161 offset:76
	ds_read_b32 v177, v161 offset:72
	ds_read_b32 v178, v161 offset:68
	ds_read_b32 v179, v161 offset:64
	ds_read_b32 v180, v161 offset:28
	ds_read_b32 v181, v161 offset:24
	ds_read_b32 v182, v161 offset:20
	ds_read_b32 v183, v161 offset:16
	ds_read_b32 v184, v161 offset:12
	ds_read_b32 v185, v161 offset:8
	ds_read_b32 v186, v161 offset:4
	ds_read_b32 v187, v161 offset:0
	ds_read_b32 v188, v161 offset:220
	ds_read_b32 v189, v161 offset:216
	ds_read_b32 v190, v161 offset:212
	ds_read_b32 v191, v161 offset:208
	ds_read_b32 v192, v161 offset:204
	ds_read_b32 v193, v161 offset:200
	ds_read_b32 v194, v161 offset:196
	ds_read_b32 v195, v161 offset:192
	ds_read_b32 v196, v161 offset:156
	ds_read_b32 v197, v161 offset:152
	ds_read_b32 v198, v161 offset:148
	ds_read_b32 v199, v161 offset:144
	ds_read_b32 v216, v161 offset:140
	ds_read_b32 v217, v161 offset:136
	ds_read_b32 v218, v161 offset:132
	ds_read_b32 v219, v161 offset:128
	s_waitcnt lgkmcnt(0)
	v_add_f32_e32 v64, v64, v172
	v_add_f32_e32 v65, v65, v173
	v_add_f32_e32 v66, v66, v174
	v_add_f32_e32 v67, v67, v175
	v_add_f32_e32 v68, v68, v176
	v_add_f32_e32 v69, v69, v177
	v_add_f32_e32 v70, v70, v178
	v_add_f32_e32 v71, v71, v179
	v_add_f32_e32 v72, v72, v180
	v_add_f32_e32 v73, v73, v181
	v_add_f32_e32 v74, v74, v182
	v_add_f32_e32 v75, v75, v183
	v_add_f32_e32 v76, v76, v184
	v_add_f32_e32 v77, v77, v185
	v_add_f32_e32 v78, v78, v186
	v_add_f32_e32 v79, v79, v187
	v_add_f32_e32 v80, v80, v188
	v_add_f32_e32 v81, v81, v189
	v_add_f32_e32 v82, v82, v190
	v_add_f32_e32 v83, v83, v191
	v_add_f32_e32 v84, v84, v192
	v_add_f32_e32 v85, v85, v193
	v_add_f32_e32 v86, v86, v194
	v_add_f32_e32 v87, v87, v195
	v_add_f32_e32 v88, v88, v196
	v_add_f32_e32 v89, v89, v197
	v_add_f32_e32 v90, v90, v198
	v_add_f32_e32 v91, v91, v199
	v_add_f32_e32 v92, v92, v216
	v_add_f32_e32 v93, v93, v217
	v_add_f32_e32 v94, v94, v218
	v_add_f32_e32 v95, v95, v219

; #define ALAS __attribute__((address_space(3)))
; __device__ __forceinline__ void moba_unit(int b, int h, int j, const bf16_t* Q, const bf16_t* K, const bf16_t* VT, bf16_t* O, const float* biasd, const float* kmean, ALAS unsigned char* lds) {
;     ...
;     ALAS float* bt = (ALAS float*)(lds + 36864);
;     if (tid < 256) bt[tid] = biasd[h * 256 + tid];
;     const float cb = biasd[h * 256 + 255];
.LBB0_520:
	s_movk_i32 s0, 0xff
	s_bfe_u32 s6, s36, 0x40001
	v_cmp_lt_i32_e32 vcc, s0, v10
	s_and_saveexec_b64 s[0:1], vcc
	s_xor_b64 s[0:1], exec, s[0:1]
	s_lshl_b32 s4, s6, 8
	s_or_saveexec_b64 s[0:1], s[0:1]
	v_mov_b32_e32 v144, s4
	s_xor_b64 exec, exec, s[0:1]
	s_cbranch_execz .LBB0_524
	s_lshl_b32 s4, s6, 8
	v_add_u32_e32 v0, s4, v10
	s_waitcnt lgkmcnt(0)
	v_ashrrev_i32_e32 v1, 31, v0
	v_lshl_add_u64 v[0:1], v[0:1], 2, s[96:97]
	global_load_dword v0, v[0:1], off
	v_lshl_add_u32 v2, v10, 2, 0
	v_mov_b32_e32 v144, s4
	s_waitcnt vmcnt(0)
	ds_write_b32 v2, v0 offset:36864
	ds_write_b32 v2, v0 offset:44032
	ds_write_b32 v2, v205 offset:43008

; #define ALAS __attribute__((address_space(3)))
; __device__ __forceinline__ void near_bias(f32x16& s0, f32x16& s1, const ALAS float* bt, int qpos, int kbase, int hi) {
; #pragma unroll
;     for (int r = 0; r < 16; ++r) {
;         const int d0 = qpos - (kbase + (r & 7) + 8 * hi + 16 * (r >> 3)), d1 = d0 - 32;
;         const float b0 = bt[min(max(d0, 0), 255)], b1 = bt[min(max(d1, 0), 255)];
;         s0[r] = d0 < 0 ? NEG : s0[r] + b0; s1[r] = d1 < 0 ? NEG : s1[r] + b1;
;     }
; }
; __device__ __forceinline__ void moba_unit(int b, int h, int j, const bf16_t* Q, const bf16_t* K, const bf16_t* VT, bf16_t* O, const float* biasd, const float* kmean, ALAS unsigned char* lds) {
;     ...
;         const bool own = t < 4; const int n = own ? j : ((t - 4) >> 2); const int kbase = own ? (256 * j + 64 * t) : (64 * (t - 4));
;         const bool sel = own ? true : (((selmask >> n) & 1u) != 0u);
;         const bool active = own ? (64 * t <= 32 * wid + 31) : (__any(sel) != 0);
;         if (active) {
;             const bool nearb = (q0 - (kbase + 63)) < 128;
;             f32x16 s0, s1; const float ci = sel ? ((nearb ? 0.f : cb) - mref) : NEG;
;             qk_tile(s0, s1, ci, buf, qf, r32, hi);
;             if (nearb) near_bias(s0, s1, bt, qpos, kbase, hi);
.LBB0_542:
	s_add_i32 s10, s18, 0x100
	s_and_b64 s[8:9], s[6:7], exec
	s_cselect_b32 s8, s10, s15
	s_or_b64 vcc, s[6:7], s[0:1]
	s_sub_i32 s0, s4, s8
	s_cmpk_gt_i32 s0, 0x7f
	s_cselect_b64 s[0:1], -1, 0
	v_cndmask_b32_e64 v32, 0, v99, s[0:1]
	v_sub_f32_e32 v32, v32, v101
	v_cndmask_b32_e32 v32, v205, v32, vcc
	v_mov_b32_e32 v33, v32
	v_mov_b32_e32 v34, v32
	v_mov_b32_e32 v35, v32
	v_mov_b32_e32 v36, v32
	v_mov_b32_e32 v37, v32
	v_mov_b32_e32 v38, v32
	v_mov_b32_e32 v39, v32
	v_mov_b32_e32 v40, v32
	v_mov_b32_e32 v41, v32
	v_mov_b32_e32 v42, v32
	v_mov_b32_e32 v43, v32
	v_mov_b32_e32 v44, v32
	v_mov_b32_e32 v45, v32
	v_mov_b32_e32 v46, v32
	v_mov_b32_e32 v47, v32
	s_waitcnt lgkmcnt(6)
	s_nop 1
	v_mfma_f32_32x32x16_bf16 v[48:63], v[108:111], v[64:67], v[32:47]
	s_and_b64 vcc, exec, s[0:1]
	v_mfma_f32_32x32x16_bf16 v[32:47], v[112:115], v[64:67], v[32:47]
	s_waitcnt lgkmcnt(4)
	v_mfma_f32_32x32x16_bf16 v[48:63], v[116:119], v[68:71], v[48:63]
	v_mfma_f32_32x32x16_bf16 v[32:47], v[120:123], v[68:71], v[32:47]
	s_waitcnt lgkmcnt(2)
	v_mfma_f32_32x32x16_bf16 v[48:63], v[124:127], v[72:75], v[48:63]
	v_mfma_f32_32x32x16_bf16 v[32:47], v[128:131], v[72:75], v[32:47]
	s_waitcnt lgkmcnt(0)
	v_mfma_f32_32x32x16_bf16 v[48:63], v[132:135], v[76:79], v[48:63]
	v_mfma_f32_32x32x16_bf16 v[32:47], v[136:139], v[76:79], v[32:47]
	s_cbranch_vccnz .LBB0_544
	v_or_b32_e32 v140, s8, v98
	v_sub_u32_e32 v140, v90, v140
	v_lshlrev_b32_e32 v140, 2, v140
	v_add_u32_e32 v140, 0xab24, v140
	ds_read_b32 v108, v140 offset:92
	ds_read_b32 v109, v140 offset:88
	ds_read_b32 v110, v140 offset:84
	ds_read_b32 v111, v140 offset:80
	ds_read_b32 v112, v140 offset:76
	ds_read_b32 v113, v140 offset:72
	ds_read_b32 v114, v140 offset:68
	ds_read_b32 v115, v140 offset:64
	ds_read_b32 v116, v140 offset:28
	ds_read_b32 v117, v140 offset:24
	ds_read_b32 v118, v140 offset:20
	ds_read_b32 v119, v140 offset:16
	ds_read_b32 v120, v140 offset:12
	ds_read_b32 v121, v140 offset:8
	ds_read_b32 v122, v140 offset:4
	ds_read_b32 v123, v140 offset:0
	ds_read_b32 v124, v140 offset:220
	ds_read_b32 v125, v140 offset:216
	ds_read_b32 v126, v140 offset:212
	ds_read_b32 v127, v140 offset:208
	ds_read_b32 v128, v140 offset:204
	ds_read_b32 v129, v140 offset:200
	ds_read_b32 v130, v140 offset:196
	ds_read_b32 v131, v140 offset:192
	ds_read_b32 v132, v140 offset:156
	ds_read_b32 v133, v140 offset:152
	ds_read_b32 v134, v140 offset:148
	ds_read_b32 v135, v140 offset:144
	ds_read_b32 v136, v140 offset:140
	ds_read_b32 v137, v140 offset:136
	ds_read_b32 v138, v140 offset:132
	ds_read_b32 v139, v140 offset:128
	s_waitcnt lgkmcnt(0)
	v_add_f32_e32 v32, v32, v108
	v_add_f32_e32 v33, v33, v109
	v_add_f32_e32 v34, v34, v110
	v_add_f32_e32 v35, v35, v111
	v_add_f32_e32 v36, v36, v112
	v_add_f32_e32 v37, v37, v113
	v_add_f32_e32 v38, v38, v114
	v_add_f32_e32 v39, v39, v115
	v_add_f32_e32 v40, v40, v116
	v_add_f32_e32 v41, v41, v117
	v_add_f32_e32 v42, v42, v118
	v_add_f32_e32 v43, v43, v119
	v_add_f32_e32 v44, v44, v120
	v_add_f32_e32 v45, v45, v121
	v_add_f32_e32 v46, v46, v122
	v_add_f32_e32 v47, v47, v123
	v_add_f32_e32 v48, v48, v124
	v_add_f32_e32 v49, v49, v125
	v_add_f32_e32 v50, v50, v126
	v_add_f32_e32 v51, v51, v127
	v_add_f32_e32 v52, v52, v128
	v_add_f32_e32 v53, v53, v129
	v_add_f32_e32 v54, v54, v130
	v_add_f32_e32 v55, v55, v131
	v_add_f32_e32 v56, v56, v132
	v_add_f32_e32 v57, v57, v133
	v_add_f32_e32 v58, v58, v134
	v_add_f32_e32 v59, v59, v135
	v_add_f32_e32 v60, v60, v136
	v_add_f32_e32 v61, v61, v137
	v_add_f32_e32 v62, v62, v138
	v_add_f32_e32 v63, v63, v139
